# SSD output stage: the four 16-lane sum(y^2) butterflies via DPP adds (quad_perm / row_half_mirror / row_mirror) instead of 16 ds_bpermute
# speedup vs baseline: 1.0087x; 1.0087x over previous
.LBB0_273:
	s_or_b64 exec, exec, s[84:85]
	ds_read_b32 v43, v132
	ds_read_b32 v87, v133
	s_waitcnt vmcnt(20)
	v_lshlrev_b32_e32 v84, 16, v84
	s_mov_b32 s0, 0x25f92000
	s_mov_b64 s[84:85], 0x800
	s_waitcnt lgkmcnt(1)
	v_sub_f32_e32 v44, v44, v43
	v_mul_f32_e32 v44, 0x3fb8aa3b, v44
	v_exp_f32_e32 v44, v44
	s_nop 0
	v_mul_f32_e32 v38, v38, v44
	s_waitcnt lgkmcnt(0)
	v_mul_f32_e32 v38, v87, v38
	v_cndmask_b32_e64 v38, v38, 0, s[36:37]
	v_cvt_pk_bf16_f32 v38, v38, v38
	ds_write_b16 v128, v38 offset:32
	v_sub_f32_e32 v38, v45, v43
	v_mul_f32_e32 v38, 0x3fb8aa3b, v38
	v_exp_f32_e32 v38, v38
	s_nop 0
	v_mul_f32_e32 v38, v39, v38
	v_mul_f32_e32 v38, v87, v38
	v_cndmask_b32_e64 v38, v38, 0, s[38:39]
	v_cvt_pk_bf16_f32 v38, v38, v38
	ds_write_b16 v129, v38 offset:32
	v_sub_f32_e32 v38, v85, v43
	v_mul_f32_e32 v38, 0x3fb8aa3b, v38
	v_exp_f32_e32 v38, v38
	s_nop 0
	v_mul_f32_e32 v38, v40, v38
	v_mul_f32_e32 v38, v87, v38
	v_cndmask_b32_e64 v38, v38, 0, s[40:41]
	v_cvt_pk_bf16_f32 v38, v38, v38
	ds_write_b16 v130, v38 offset:32
	v_sub_f32_e32 v38, v42, v43
	v_mul_f32_e32 v38, 0x3fb8aa3b, v38
	v_exp_f32_e32 v38, v38
	s_nop 0
	v_mul_f32_e32 v38, v41, v38
	v_mul_f32_e32 v38, v87, v38
	v_cndmask_b32_e64 v38, v38, 0, s[42:43]
	v_cvt_pk_bf16_f32 v38, v38, v38
	ds_write_b16 v131, v38 offset:32
	s_waitcnt lgkmcnt(0)
	s_barrier
	ds_read_b128 v[38:41], v90
	ds_read_b128 v[42:45], v134
	ds_read_b128 v[166:169], v110
	ds_read_b128 v[188:191], v90 offset:64
	ds_read_b128 v[208:211], v134 offset:64
	ds_read_b128 v[212:215], v110 offset:64
	ds_read_b128 v[218:221], v90 offset:128
	ds_read_b128 v[222:225], v134 offset:128
	ds_read_b128 v[226:229], v110 offset:128
	ds_read_b128 v[230:233], v90 offset:192
	ds_read_b128 v[234:237], v134 offset:192
	ds_read_b128 v[238:241], v110 offset:192
	s_waitcnt lgkmcnt(10)
	v_mfma_f32_16x16x32_bf16 v[42:45], v[38:41], v[42:45], 0
	s_waitcnt lgkmcnt(9)
	v_mfma_f32_16x16x32_bf16 v[38:41], v[38:41], v[166:169], 0
	s_waitcnt lgkmcnt(7)
	v_mfma_f32_16x16x32_bf16 v[42:45], v[188:191], v[208:211], v[42:45]
	s_waitcnt lgkmcnt(6)
	v_mfma_f32_16x16x32_bf16 v[38:41], v[188:191], v[212:215], v[38:41]
	s_waitcnt lgkmcnt(4)
	v_mfma_f32_16x16x32_bf16 v[42:45], v[218:221], v[222:225], v[42:45]
	s_waitcnt lgkmcnt(3)
	v_mfma_f32_16x16x32_bf16 v[38:41], v[218:221], v[226:229], v[38:41]
	s_waitcnt lgkmcnt(1)
	v_mfma_f32_16x16x32_bf16 v[42:45], v[230:233], v[234:237], v[42:45]
	s_waitcnt lgkmcnt(0)
	v_mfma_f32_16x16x32_bf16 v[38:41], v[230:233], v[238:241], v[38:41]
	ds_read2_b32 v[166:167], v105 offset1:1
	ds_read2_b32 v[242:243], v107 offset1:1
	ds_read_b128 v[208:211], v91
	ds_read_b128 v[188:191], v135 offset:53248
	ds_read_b128 v[212:215], v111 offset:53248
	ds_read_b128 v[218:221], v91 offset:64
	ds_read_b128 v[222:225], v136 offset:53248
	ds_read_b128 v[226:229], v112 offset:53248
	s_waitcnt lgkmcnt(6)
	v_mul_f32_e32 v85, 0x3fb8aa3b, v166
	v_exp_f32_e32 v170, v85
	v_mul_f32_e32 v85, 0x3fb8aa3b, v167
	v_exp_f32_e32 v171, v85
	v_mul_f32_e32 v85, 0x3fb8aa3b, v242
	v_exp_f32_e32 v192, v85
	v_mul_f32_e32 v85, 0x3fb8aa3b, v243
	v_exp_f32_e32 v193, v85
	s_nop 0
	ds_read_u16 v85, v137 offset:53248
	ds_read_u16 v194, v138 offset:53248
	ds_read_u16 v195, v139 offset:53248
	ds_read_u16 v196, v140 offset:53248
	ds_read_u16 v197, v113 offset:53248
	ds_read_u16 v198, v114 offset:53248
	ds_read_u16 v199, v115 offset:53248
	ds_read_u16 v200, v116 offset:53248
	v_pk_mul_f32 v[42:43], v[42:43], v[170:171]
	v_pk_mul_f32 v[38:39], v[38:39], v[170:171]
	v_pk_mul_f32 v[44:45], v[44:45], v[192:193]
	v_pk_mul_f32 v[40:41], v[40:41], v[192:193]
	s_waitcnt lgkmcnt(12)
	v_mfma_f32_16x16x32_bf16 v[42:45], v[208:211], v[188:191], v[42:45]
	s_waitcnt lgkmcnt(11)
	v_mfma_f32_16x16x32_bf16 v[38:41], v[208:211], v[212:215], v[38:41]
	s_waitcnt lgkmcnt(9)
	v_mfma_f32_16x16x32_bf16 v[42:45], v[218:221], v[222:225], v[42:45]
	s_waitcnt lgkmcnt(8)
	v_mfma_f32_16x16x32_bf16 v[38:41], v[218:221], v[226:229], v[38:41]
	s_waitcnt lgkmcnt(0)
	v_lshlrev_b32_e32 v85, 16, v85
	v_lshl_add_u64 v[166:167], s[50:51], 0, v[72:73]
	s_nop 3
	v_fma_f32 v42, v51, v85, v42
	v_mul_f32_e32 v85, 0xbfb8aa3b, v84
	v_exp_f32_e32 v85, v85
	v_add_co_u32_e32 v168, vcc, s0, v166
	s_mov_b64 s[0:1], 0x1000
	v_add_f32_e32 v85, 1.0, v85
	v_rcp_f32_e32 v85, v85
	v_addc_co_u32_e32 v169, vcc, 0, v167, vcc
	v_mul_f32_e32 v84, v85, v84
	v_mul_f32_e32 v144, v84, v42
	v_cvt_pk_bf16_f32 v42, v144, v144
	global_store_short v[168:169], v42, off offset:-4096
	v_mov_b32_e32 v42, v194
	v_lshl_add_u64 v[84:85], v[82:83], 0, s[56:57]
	s_waitcnt lgkmcnt(0)
	v_lshlrev_b32_e32 v42, 16, v42
	v_fma_f32 v42, v51, v42, v43
	s_waitcnt vmcnt(20)
	v_lshlrev_b32_e32 v43, 16, v86
	v_mul_f32_e32 v86, 0xbfb8aa3b, v43
	v_exp_f32_e32 v86, v86
	s_nop 0
	v_add_f32_e32 v86, 1.0, v86
	v_rcp_f32_e32 v86, v86
	s_nop 0
	v_mul_f32_e32 v43, v86, v43
	v_mul_f32_e32 v165, v43, v42
	v_cvt_pk_bf16_f32 v42, v165, v165
	global_store_short v[168:169], v42, off
	v_mov_b32_e32 v42, v195
	s_waitcnt vmcnt(20)
	v_lshlrev_b32_e32 v43, 16, v164
	v_lshl_add_u64 v[86:87], v[84:85], 0, s[84:85]
	v_or_b32_e32 v86, v86, v66
	s_waitcnt lgkmcnt(0)
	v_lshlrev_b32_e32 v42, 16, v42
	v_fma_f32 v42, v51, v42, v44
	v_mul_f32_e32 v44, 0xbfb8aa3b, v43
	v_exp_f32_e32 v44, v44
	s_nop 0
	v_add_f32_e32 v44, 1.0, v44
	v_rcp_f32_e32 v44, v44
	s_nop 0
	v_mul_f32_e32 v43, v44, v43
	v_mul_f32_e32 v164, v43, v42
	v_lshl_add_u64 v[42:43], v[84:85], 0, s[0:1]
	s_mov_b32 s0, 0x25f94000
	v_add_co_u32_e32 v166, vcc, s0, v166
	v_cvt_pk_bf16_f32 v44, v164, v164
	s_mov_b64 s[0:1], 0x1800
	s_nop 0
	v_addc_co_u32_e32 v167, vcc, 0, v167, vcc
	global_store_short v[166:167], v44, off offset:-4096
	v_mov_b32_e32 v44, v196
	v_or_b32_e32 v42, v42, v66
	v_lshl_add_u64 v[42:43], v[42:43], 1, s[74:75]
	s_waitcnt lgkmcnt(0)
	v_lshlrev_b32_e32 v44, 16, v44
	v_fmac_f32_e32 v45, v51, v44
	s_waitcnt vmcnt(20)
	v_lshlrev_b32_e32 v44, 16, v163
	v_mul_f32_e32 v145, 0xbfb8aa3b, v44
	v_exp_f32_e32 v145, v145
	s_nop 0
	v_add_f32_e32 v145, 1.0, v145
	v_rcp_f32_e32 v145, v145
	s_nop 0
	v_mul_f32_e32 v44, v145, v44
	v_mul_f32_e32 v163, v44, v45
	v_cvt_pk_bf16_f32 v145, v163, v163
	global_store_short v[166:167], v145, off
	v_mov_b32_e32 v145, v197
	v_lshl_add_u64 v[44:45], v[84:85], 0, s[0:1]
	v_or_b32_e32 v84, v84, v66
	v_lshl_add_u64 v[84:85], v[84:85], 1, s[74:75]
	v_or_b32_e32 v44, v44, v66
	s_waitcnt lgkmcnt(0)
	v_lshlrev_b32_e32 v145, 16, v145
	v_fma_f32 v38, v51, v145, v38
	s_waitcnt vmcnt(20)
	v_lshlrev_b32_e32 v145, 16, v160
	v_mul_f32_e32 v146, 0xbfb8aa3b, v145
	v_exp_f32_e32 v146, v146
	s_nop 0
	v_add_f32_e32 v146, 1.0, v146
	v_rcp_f32_e32 v146, v146
	s_nop 0
	v_mul_f32_e32 v145, v146, v145
	v_mul_f32_e32 v38, v145, v38
	v_cvt_pk_bf16_f32 v145, v38, v38
	global_store_short v[84:85], v145, off
	v_mul_f32_e32 v145, v38, v38
	v_mov_b32_e32 v38, v198
	v_fmac_f32_e32 v145, v144, v144
	s_waitcnt lgkmcnt(0)
	v_lshlrev_b32_e32 v38, 16, v38
	v_fma_f32 v38, v51, v38, v39
	s_waitcnt vmcnt(18)
	v_lshlrev_b32_e32 v39, 16, v154
	v_mul_f32_e32 v84, 0xbfb8aa3b, v39
	v_exp_f32_e32 v84, v84
	s_nop 0
	v_add_f32_e32 v84, 1.0, v84
	v_rcp_f32_e32 v84, v84
	s_nop 0
	v_mul_f32_e32 v39, v84, v39
	v_mul_f32_e32 v38, v39, v38
	v_cvt_pk_bf16_f32 v39, v38, v38
	v_lshl_add_u64 v[84:85], v[86:87], 1, s[74:75]
	global_store_short v[84:85], v39, off
	v_mov_b32_e32 v39, v199
	s_waitcnt lgkmcnt(0)
	v_lshlrev_b32_e32 v39, 16, v39
	v_fma_f32 v39, v51, v39, v40
	v_lshlrev_b32_e32 v40, 16, v153
	v_mul_f32_e32 v84, 0xbfb8aa3b, v40
	v_exp_f32_e32 v84, v84
	s_nop 0
	v_add_f32_e32 v84, 1.0, v84
	v_rcp_f32_e32 v84, v84
	s_nop 0
	v_mul_f32_e32 v40, v84, v40
	v_mul_f32_e32 v39, v40, v39
	v_cvt_pk_bf16_f32 v40, v39, v39
	global_store_short v[42:43], v40, off
	v_mov_b32_e32 v40, v200
	s_waitcnt lgkmcnt(0)
	v_lshlrev_b32_e32 v40, 16, v40
	v_fmac_f32_e32 v41, v51, v40
	v_lshlrev_b32_e32 v40, 16, v141
	v_mul_f32_e32 v42, 0xbfb8aa3b, v40
	v_exp_f32_e32 v42, v42
	s_nop 0
	v_add_f32_e32 v42, 1.0, v42
	v_rcp_f32_e32 v42, v42
	s_nop 0
	v_mul_f32_e32 v40, v42, v40
	v_lshl_add_u64 v[42:43], v[44:45], 1, s[74:75]
	v_mul_f32_e32 v40, v40, v41
	v_cvt_pk_bf16_f32 v41, v40, v40
	global_store_short v[42:43], v41, off
	v_and_b32_e32 v42, 64, v177
	v_xor_b32_e32 v41, 1, v177
	v_add_u32_e32 v44, 64, v42
	v_cmp_lt_i32_e32 vcc, v41, v44
	v_xor_b32_e32 v42, 2, v177
	v_xor_b32_e32 v43, 4, v177
	v_cndmask_b32_e32 v41, v177, v41, vcc
	v_cmp_lt_i32_e32 vcc, v42, v44
	v_xor_b32_e32 v45, 8, v177
	v_lshlrev_b32_e32 v41, 2, v41
	v_cndmask_b32_e32 v42, v177, v42, vcc
	v_cmp_lt_i32_e32 vcc, v43, v44
	v_lshlrev_b32_e32 v42, 2, v42
	s_nop 0
	v_cndmask_b32_e32 v43, v177, v43, vcc
	v_cmp_lt_i32_e32 vcc, v45, v44
	v_lshlrev_b32_e32 v43, 2, v43
	s_nop 0
	v_cndmask_b32_e32 v44, v177, v45, vcc
	v_lshlrev_b32_e32 v44, 2, v44
	v_mul_f32_e32 v201, v38, v38
	v_fmac_f32_e32 v201, v165, v165
	v_mul_f32_e32 v202, v39, v39
	v_fmac_f32_e32 v202, v164, v164
	v_mul_f32_e32 v203, v40, v40
	v_fmac_f32_e32 v203, v163, v163
	v_add_f32_dpp v145, v145, v145 quad_perm:[1,0,3,2] row_mask:0xf bank_mask:0xf
	v_add_f32_dpp v201, v201, v201 quad_perm:[1,0,3,2] row_mask:0xf bank_mask:0xf
	v_add_f32_dpp v202, v202, v202 quad_perm:[1,0,3,2] row_mask:0xf bank_mask:0xf
	v_add_f32_dpp v203, v203, v203 quad_perm:[1,0,3,2] row_mask:0xf bank_mask:0xf
	v_add_f32_dpp v145, v145, v145 quad_perm:[2,3,0,1] row_mask:0xf bank_mask:0xf
	v_add_f32_dpp v201, v201, v201 quad_perm:[2,3,0,1] row_mask:0xf bank_mask:0xf
	v_add_f32_dpp v202, v202, v202 quad_perm:[2,3,0,1] row_mask:0xf bank_mask:0xf
	v_add_f32_dpp v203, v203, v203 quad_perm:[2,3,0,1] row_mask:0xf bank_mask:0xf
	v_add_f32_dpp v145, v145, v145 row_half_mirror row_mask:0xf bank_mask:0xf
	v_add_f32_dpp v201, v201, v201 row_half_mirror row_mask:0xf bank_mask:0xf
	v_add_f32_dpp v202, v202, v202 row_half_mirror row_mask:0xf bank_mask:0xf
	v_add_f32_dpp v203, v203, v203 row_half_mirror row_mask:0xf bank_mask:0xf
	v_add_f32_dpp v145, v145, v145 row_mirror row_mask:0xf bank_mask:0xf
	v_add_f32_dpp v201, v201, v201 row_mirror row_mask:0xf bank_mask:0xf
	v_add_f32_dpp v202, v202, v202 row_mirror row_mask:0xf bank_mask:0xf
	v_add_f32_dpp v203, v203, v203 row_mirror row_mask:0xf bank_mask:0xf
	s_and_saveexec_b64 s[84:85], s[8:9]
	s_cbranch_execz .LBB0_259
	ds_write_b32 v117, v145
	ds_write_b32 v117, v201 offset:4
	ds_write_b32 v117, v202 offset:8
	ds_write_b32 v117, v203 offset:12
	s_branch .LBB0_259
